# band epilogue rcp/16 loads in flight + LN residual 4 groups in flight
# speedup vs baseline: 1.0131x; 1.0131x over previous
.LBB0_374:
	v_lshlrev_b32_e32 v125, 1, v138
	v_mad_u32_u24 v122, v192, s59, v125
	v_lshl_add_u32 v124, v192, 12, v125
	s_add_u32 s14, s4, s0
	s_addc_u32 s15, s5, s1
	s_add_u32 s14, s14, 0x1000
	s_addc_u32 s15, s15, 0
	s_add_u32 s38, s56, s0
	s_addc_u32 s39, s57, s1
	v_add_u32_e32 v123, 0x2a000, v122
	v_add_u32_e32 v125, 0x10000, v124
	global_load_dwordx2 v[86:87], v122, s[14:15] nt
	global_load_dwordx2 v[88:89], v122, s[14:15] offset:32 nt
	global_load_dwordx2 v[90:91], v122, s[14:15] offset:64 nt
	global_load_dwordx2 v[92:93], v122, s[14:15] offset:96 nt
	global_load_dwordx2 v[94:95], v122, s[14:15] offset:128 nt
	global_load_dwordx2 v[96:97], v122, s[14:15] offset:160 nt
	global_load_dwordx2 v[98:99], v122, s[14:15] offset:192 nt
	global_load_dwordx2 v[100:101], v122, s[14:15] offset:224 nt
	global_load_dwordx2 v[102:103], v123, s[14:15] nt
	global_load_dwordx2 v[104:105], v123, s[14:15] offset:32 nt
	global_load_dwordx2 v[106:107], v123, s[14:15] offset:64 nt
	global_load_dwordx2 v[108:109], v123, s[14:15] offset:96 nt
	global_load_dwordx2 v[110:111], v123, s[14:15] offset:128 nt
	global_load_dwordx2 v[112:113], v123, s[14:15] offset:160 nt
	global_load_dwordx2 v[114:115], v123, s[14:15] offset:192 nt
	global_load_dwordx2 v[116:117], v123, s[14:15] offset:224 nt
	v_rcp_f32_e32 v118, v126
	v_rcp_f32_e32 v119, v34
	s_nop 0
	v_fma_f32 v0, -v126, v118, 1.0
	v_fma_f32 v120, -v34, v119, 1.0
	v_fmac_f32_e32 v118, v0, v118
	v_fmac_f32_e32 v119, v120, v119
	v_mov_b32_e32 v0, v118
	v_mov_b32_e32 v120, v119
	s_waitcnt vmcnt(15)
	v_lshlrev_b32_e32 v66, 16, v86
	v_and_b32_e32 v67, 0xffff0000, v86
	v_lshlrev_b32_e32 v68, 16, v87
	v_and_b32_e32 v69, 0xffff0000, v87
	v_mul_f32_e32 v70, 0xbfb8aa3b, v66
	v_mul_f32_e32 v71, 0xbfb8aa3b, v67
	v_mul_f32_e32 v72, 0xbfb8aa3b, v68
	v_mul_f32_e32 v73, 0xbfb8aa3b, v69
	v_exp_f32_e32 v70, v70
	v_exp_f32_e32 v71, v71
	v_exp_f32_e32 v72, v72
	v_exp_f32_e32 v73, v73
	v_pk_mul_f32 v[78:79], v[82:83], v[0:1] op_sel_hi:[1,0]
	v_pk_add_f32 v[70:71], v[70:71], 1.0 op_sel_hi:[1,0]
	v_pk_add_f32 v[72:73], v[72:73], 1.0 op_sel_hi:[1,0]
	v_rcp_f32_e32 v74, v70
	v_rcp_f32_e32 v75, v71
	v_rcp_f32_e32 v76, v72
	v_rcp_f32_e32 v77, v73
	v_pk_mul_f32 v[80:81], v[84:85], v[0:1] op_sel_hi:[1,0]
	v_pk_mul_f32 v[74:75], v[66:67], v[74:75]
	v_pk_mul_f32 v[76:77], v[68:69], v[76:77]
	v_pk_mul_f32 v[78:79], v[78:79], v[74:75]
	v_pk_mul_f32 v[80:81], v[80:81], v[76:77]
	v_cvt_pk_bf16_f32 v70, v78, v79
	v_cvt_pk_bf16_f32 v71, v80, v81
	global_store_dwordx2 v124, v[70:71], s[38:39]
	s_waitcnt vmcnt(15)
	v_lshlrev_b32_e32 v66, 16, v88
	v_and_b32_e32 v67, 0xffff0000, v88
	v_lshlrev_b32_e32 v68, 16, v89
	v_and_b32_e32 v69, 0xffff0000, v89
	v_mul_f32_e32 v70, 0xbfb8aa3b, v66
	v_mul_f32_e32 v71, 0xbfb8aa3b, v67
	v_mul_f32_e32 v72, 0xbfb8aa3b, v68
	v_mul_f32_e32 v73, 0xbfb8aa3b, v69
	v_exp_f32_e32 v70, v70
	v_exp_f32_e32 v71, v71
	v_exp_f32_e32 v72, v72
	v_exp_f32_e32 v73, v73
	v_pk_mul_f32 v[78:79], v[62:63], v[0:1] op_sel_hi:[1,0]
	v_pk_add_f32 v[70:71], v[70:71], 1.0 op_sel_hi:[1,0]
	v_pk_add_f32 v[72:73], v[72:73], 1.0 op_sel_hi:[1,0]
	v_rcp_f32_e32 v74, v70
	v_rcp_f32_e32 v75, v71
	v_rcp_f32_e32 v76, v72
	v_rcp_f32_e32 v77, v73
	v_pk_mul_f32 v[80:81], v[64:65], v[0:1] op_sel_hi:[1,0]
	v_pk_mul_f32 v[74:75], v[66:67], v[74:75]
	v_pk_mul_f32 v[76:77], v[68:69], v[76:77]
	v_pk_mul_f32 v[78:79], v[78:79], v[74:75]
	v_pk_mul_f32 v[80:81], v[80:81], v[76:77]
	v_cvt_pk_bf16_f32 v70, v78, v79
	v_cvt_pk_bf16_f32 v71, v80, v81
	global_store_dwordx2 v124, v[70:71], s[38:39] offset:32
	s_waitcnt vmcnt(15)
	v_lshlrev_b32_e32 v66, 16, v90
	v_and_b32_e32 v67, 0xffff0000, v90
	v_lshlrev_b32_e32 v68, 16, v91
	v_and_b32_e32 v69, 0xffff0000, v91
	v_mul_f32_e32 v70, 0xbfb8aa3b, v66
	v_mul_f32_e32 v71, 0xbfb8aa3b, v67
	v_mul_f32_e32 v72, 0xbfb8aa3b, v68
	v_mul_f32_e32 v73, 0xbfb8aa3b, v69
	v_exp_f32_e32 v70, v70
	v_exp_f32_e32 v71, v71
	v_exp_f32_e32 v72, v72
	v_exp_f32_e32 v73, v73
	v_pk_mul_f32 v[78:79], v[58:59], v[0:1] op_sel_hi:[1,0]
	v_pk_add_f32 v[70:71], v[70:71], 1.0 op_sel_hi:[1,0]
	v_pk_add_f32 v[72:73], v[72:73], 1.0 op_sel_hi:[1,0]
	v_rcp_f32_e32 v74, v70
	v_rcp_f32_e32 v75, v71
	v_rcp_f32_e32 v76, v72
	v_rcp_f32_e32 v77, v73
	v_pk_mul_f32 v[80:81], v[60:61], v[0:1] op_sel_hi:[1,0]
	v_pk_mul_f32 v[74:75], v[66:67], v[74:75]
	v_pk_mul_f32 v[76:77], v[68:69], v[76:77]
	v_pk_mul_f32 v[78:79], v[78:79], v[74:75]
	v_pk_mul_f32 v[80:81], v[80:81], v[76:77]
	v_cvt_pk_bf16_f32 v70, v78, v79
	v_cvt_pk_bf16_f32 v71, v80, v81
	global_store_dwordx2 v124, v[70:71], s[38:39] offset:64
	s_waitcnt vmcnt(15)
	v_lshlrev_b32_e32 v66, 16, v92
	v_and_b32_e32 v67, 0xffff0000, v92
	v_lshlrev_b32_e32 v68, 16, v93
	v_and_b32_e32 v69, 0xffff0000, v93
	v_mul_f32_e32 v70, 0xbfb8aa3b, v66
	v_mul_f32_e32 v71, 0xbfb8aa3b, v67
	v_mul_f32_e32 v72, 0xbfb8aa3b, v68
	v_mul_f32_e32 v73, 0xbfb8aa3b, v69
	v_exp_f32_e32 v70, v70
	v_exp_f32_e32 v71, v71
	v_exp_f32_e32 v72, v72
	v_exp_f32_e32 v73, v73
	v_pk_mul_f32 v[78:79], v[54:55], v[0:1] op_sel_hi:[1,0]
	v_pk_add_f32 v[70:71], v[70:71], 1.0 op_sel_hi:[1,0]
	v_pk_add_f32 v[72:73], v[72:73], 1.0 op_sel_hi:[1,0]
	v_rcp_f32_e32 v74, v70
	v_rcp_f32_e32 v75, v71
	v_rcp_f32_e32 v76, v72
	v_rcp_f32_e32 v77, v73
	v_pk_mul_f32 v[80:81], v[56:57], v[0:1] op_sel_hi:[1,0]
	v_pk_mul_f32 v[74:75], v[66:67], v[74:75]
	v_pk_mul_f32 v[76:77], v[68:69], v[76:77]
	v_pk_mul_f32 v[78:79], v[78:79], v[74:75]
	v_pk_mul_f32 v[80:81], v[80:81], v[76:77]
	v_cvt_pk_bf16_f32 v70, v78, v79
	v_cvt_pk_bf16_f32 v71, v80, v81
	global_store_dwordx2 v124, v[70:71], s[38:39] offset:96
	s_waitcnt vmcnt(15)
	v_lshlrev_b32_e32 v66, 16, v94
	v_and_b32_e32 v67, 0xffff0000, v94
	v_lshlrev_b32_e32 v68, 16, v95
	v_and_b32_e32 v69, 0xffff0000, v95
	v_mul_f32_e32 v70, 0xbfb8aa3b, v66
	v_mul_f32_e32 v71, 0xbfb8aa3b, v67
	v_mul_f32_e32 v72, 0xbfb8aa3b, v68
	v_mul_f32_e32 v73, 0xbfb8aa3b, v69
	v_exp_f32_e32 v70, v70
	v_exp_f32_e32 v71, v71
	v_exp_f32_e32 v72, v72
	v_exp_f32_e32 v73, v73
	v_pk_mul_f32 v[78:79], v[50:51], v[0:1] op_sel_hi:[1,0]
	v_pk_add_f32 v[70:71], v[70:71], 1.0 op_sel_hi:[1,0]
	v_pk_add_f32 v[72:73], v[72:73], 1.0 op_sel_hi:[1,0]
	v_rcp_f32_e32 v74, v70
	v_rcp_f32_e32 v75, v71
	v_rcp_f32_e32 v76, v72
	v_rcp_f32_e32 v77, v73
	v_pk_mul_f32 v[80:81], v[52:53], v[0:1] op_sel_hi:[1,0]
	v_pk_mul_f32 v[74:75], v[66:67], v[74:75]
	v_pk_mul_f32 v[76:77], v[68:69], v[76:77]
	v_pk_mul_f32 v[78:79], v[78:79], v[74:75]
	v_pk_mul_f32 v[80:81], v[80:81], v[76:77]
	v_cvt_pk_bf16_f32 v70, v78, v79
	v_cvt_pk_bf16_f32 v71, v80, v81
	global_store_dwordx2 v124, v[70:71], s[38:39] offset:128
	s_waitcnt vmcnt(15)
	v_lshlrev_b32_e32 v66, 16, v96
	v_and_b32_e32 v67, 0xffff0000, v96
	v_lshlrev_b32_e32 v68, 16, v97
	v_and_b32_e32 v69, 0xffff0000, v97
	v_mul_f32_e32 v70, 0xbfb8aa3b, v66
	v_mul_f32_e32 v71, 0xbfb8aa3b, v67
	v_mul_f32_e32 v72, 0xbfb8aa3b, v68
	v_mul_f32_e32 v73, 0xbfb8aa3b, v69
	v_exp_f32_e32 v70, v70
	v_exp_f32_e32 v71, v71
	v_exp_f32_e32 v72, v72
	v_exp_f32_e32 v73, v73
	v_pk_mul_f32 v[78:79], v[46:47], v[0:1] op_sel_hi:[1,0]
	v_pk_add_f32 v[70:71], v[70:71], 1.0 op_sel_hi:[1,0]
	v_pk_add_f32 v[72:73], v[72:73], 1.0 op_sel_hi:[1,0]
	v_rcp_f32_e32 v74, v70
	v_rcp_f32_e32 v75, v71
	v_rcp_f32_e32 v76, v72
	v_rcp_f32_e32 v77, v73
	v_pk_mul_f32 v[80:81], v[48:49], v[0:1] op_sel_hi:[1,0]
	v_pk_mul_f32 v[74:75], v[66:67], v[74:75]
	v_pk_mul_f32 v[76:77], v[68:69], v[76:77]
	v_pk_mul_f32 v[78:79], v[78:79], v[74:75]
	v_pk_mul_f32 v[80:81], v[80:81], v[76:77]
	v_cvt_pk_bf16_f32 v70, v78, v79
	v_cvt_pk_bf16_f32 v71, v80, v81
	global_store_dwordx2 v124, v[70:71], s[38:39] offset:160
	s_waitcnt vmcnt(15)
	v_lshlrev_b32_e32 v66, 16, v98
	v_and_b32_e32 v67, 0xffff0000, v98
	v_lshlrev_b32_e32 v68, 16, v99
	v_and_b32_e32 v69, 0xffff0000, v99
	v_mul_f32_e32 v70, 0xbfb8aa3b, v66
	v_mul_f32_e32 v71, 0xbfb8aa3b, v67
	v_mul_f32_e32 v72, 0xbfb8aa3b, v68
	v_mul_f32_e32 v73, 0xbfb8aa3b, v69
	v_exp_f32_e32 v70, v70
	v_exp_f32_e32 v71, v71
	v_exp_f32_e32 v72, v72
	v_exp_f32_e32 v73, v73
	v_pk_mul_f32 v[78:79], v[42:43], v[0:1] op_sel_hi:[1,0]
	v_pk_add_f32 v[70:71], v[70:71], 1.0 op_sel_hi:[1,0]
	v_pk_add_f32 v[72:73], v[72:73], 1.0 op_sel_hi:[1,0]
	v_rcp_f32_e32 v74, v70
	v_rcp_f32_e32 v75, v71
	v_rcp_f32_e32 v76, v72
	v_rcp_f32_e32 v77, v73
	v_pk_mul_f32 v[80:81], v[44:45], v[0:1] op_sel_hi:[1,0]
	v_pk_mul_f32 v[74:75], v[66:67], v[74:75]
	v_pk_mul_f32 v[76:77], v[68:69], v[76:77]
	v_pk_mul_f32 v[78:79], v[78:79], v[74:75]
	v_pk_mul_f32 v[80:81], v[80:81], v[76:77]
	v_cvt_pk_bf16_f32 v70, v78, v79
	v_cvt_pk_bf16_f32 v71, v80, v81
	global_store_dwordx2 v124, v[70:71], s[38:39] offset:192
	s_waitcnt vmcnt(15)
	v_lshlrev_b32_e32 v66, 16, v100
	v_and_b32_e32 v67, 0xffff0000, v100
	v_lshlrev_b32_e32 v68, 16, v101
	v_and_b32_e32 v69, 0xffff0000, v101
	v_mul_f32_e32 v70, 0xbfb8aa3b, v66
	v_mul_f32_e32 v71, 0xbfb8aa3b, v67
	v_mul_f32_e32 v72, 0xbfb8aa3b, v68
	v_mul_f32_e32 v73, 0xbfb8aa3b, v69
	v_exp_f32_e32 v70, v70
	v_exp_f32_e32 v71, v71
	v_exp_f32_e32 v72, v72
	v_exp_f32_e32 v73, v73
	v_pk_mul_f32 v[78:79], v[38:39], v[0:1] op_sel_hi:[1,0]
	v_pk_add_f32 v[70:71], v[70:71], 1.0 op_sel_hi:[1,0]
	v_pk_add_f32 v[72:73], v[72:73], 1.0 op_sel_hi:[1,0]
	v_rcp_f32_e32 v74, v70
	v_rcp_f32_e32 v75, v71
	v_rcp_f32_e32 v76, v72
	v_rcp_f32_e32 v77, v73
	v_pk_mul_f32 v[80:81], v[40:41], v[0:1] op_sel_hi:[1,0]
	v_pk_mul_f32 v[74:75], v[66:67], v[74:75]
	v_pk_mul_f32 v[76:77], v[68:69], v[76:77]
	v_pk_mul_f32 v[78:79], v[78:79], v[74:75]
	v_pk_mul_f32 v[80:81], v[80:81], v[76:77]
	v_cvt_pk_bf16_f32 v70, v78, v79
	v_cvt_pk_bf16_f32 v71, v80, v81
	global_store_dwordx2 v124, v[70:71], s[38:39] offset:224
	s_waitcnt vmcnt(15)
	v_lshlrev_b32_e32 v66, 16, v102
	v_and_b32_e32 v67, 0xffff0000, v102
	v_lshlrev_b32_e32 v68, 16, v103
	v_and_b32_e32 v69, 0xffff0000, v103
	v_mul_f32_e32 v70, 0xbfb8aa3b, v66
	v_mul_f32_e32 v71, 0xbfb8aa3b, v67
	v_mul_f32_e32 v72, 0xbfb8aa3b, v68
	v_mul_f32_e32 v73, 0xbfb8aa3b, v69
	v_exp_f32_e32 v70, v70
	v_exp_f32_e32 v71, v71
	v_exp_f32_e32 v72, v72
	v_exp_f32_e32 v73, v73
	v_pk_mul_f32 v[78:79], v[30:31], v[120:121] op_sel_hi:[1,0]
	v_pk_add_f32 v[70:71], v[70:71], 1.0 op_sel_hi:[1,0]
	v_pk_add_f32 v[72:73], v[72:73], 1.0 op_sel_hi:[1,0]
	v_rcp_f32_e32 v74, v70
	v_rcp_f32_e32 v75, v71
	v_rcp_f32_e32 v76, v72
	v_rcp_f32_e32 v77, v73
	v_pk_mul_f32 v[80:81], v[32:33], v[120:121] op_sel_hi:[1,0]
	v_pk_mul_f32 v[74:75], v[66:67], v[74:75]
	v_pk_mul_f32 v[76:77], v[68:69], v[76:77]
	v_pk_mul_f32 v[78:79], v[78:79], v[74:75]
	v_pk_mul_f32 v[80:81], v[80:81], v[76:77]
	v_cvt_pk_bf16_f32 v70, v78, v79
	v_cvt_pk_bf16_f32 v71, v80, v81
	global_store_dwordx2 v125, v[70:71], s[38:39]
	s_waitcnt vmcnt(15)
	v_lshlrev_b32_e32 v66, 16, v104
	v_and_b32_e32 v67, 0xffff0000, v104
	v_lshlrev_b32_e32 v68, 16, v105
	v_and_b32_e32 v69, 0xffff0000, v105
	v_mul_f32_e32 v70, 0xbfb8aa3b, v66
	v_mul_f32_e32 v71, 0xbfb8aa3b, v67
	v_mul_f32_e32 v72, 0xbfb8aa3b, v68
	v_mul_f32_e32 v73, 0xbfb8aa3b, v69
	v_exp_f32_e32 v70, v70
	v_exp_f32_e32 v71, v71
	v_exp_f32_e32 v72, v72
	v_exp_f32_e32 v73, v73
	v_pk_mul_f32 v[78:79], v[26:27], v[120:121] op_sel_hi:[1,0]
	v_pk_add_f32 v[70:71], v[70:71], 1.0 op_sel_hi:[1,0]
	v_pk_add_f32 v[72:73], v[72:73], 1.0 op_sel_hi:[1,0]
	v_rcp_f32_e32 v74, v70
	v_rcp_f32_e32 v75, v71
	v_rcp_f32_e32 v76, v72
	v_rcp_f32_e32 v77, v73
	v_pk_mul_f32 v[80:81], v[28:29], v[120:121] op_sel_hi:[1,0]
	v_pk_mul_f32 v[74:75], v[66:67], v[74:75]
	v_pk_mul_f32 v[76:77], v[68:69], v[76:77]
	v_pk_mul_f32 v[78:79], v[78:79], v[74:75]
	v_pk_mul_f32 v[80:81], v[80:81], v[76:77]
	v_cvt_pk_bf16_f32 v70, v78, v79
	v_cvt_pk_bf16_f32 v71, v80, v81
	global_store_dwordx2 v125, v[70:71], s[38:39] offset:32
	s_waitcnt vmcnt(15)
	v_lshlrev_b32_e32 v66, 16, v106
	v_and_b32_e32 v67, 0xffff0000, v106
	v_lshlrev_b32_e32 v68, 16, v107
	v_and_b32_e32 v69, 0xffff0000, v107
	v_mul_f32_e32 v70, 0xbfb8aa3b, v66
	v_mul_f32_e32 v71, 0xbfb8aa3b, v67
	v_mul_f32_e32 v72, 0xbfb8aa3b, v68
	v_mul_f32_e32 v73, 0xbfb8aa3b, v69
	v_exp_f32_e32 v70, v70
	v_exp_f32_e32 v71, v71
	v_exp_f32_e32 v72, v72
	v_exp_f32_e32 v73, v73
	v_pk_mul_f32 v[78:79], v[22:23], v[120:121] op_sel_hi:[1,0]
	v_pk_add_f32 v[70:71], v[70:71], 1.0 op_sel_hi:[1,0]
	v_pk_add_f32 v[72:73], v[72:73], 1.0 op_sel_hi:[1,0]
	v_rcp_f32_e32 v74, v70
	v_rcp_f32_e32 v75, v71
	v_rcp_f32_e32 v76, v72
	v_rcp_f32_e32 v77, v73
	v_pk_mul_f32 v[80:81], v[24:25], v[120:121] op_sel_hi:[1,0]
	v_pk_mul_f32 v[74:75], v[66:67], v[74:75]
	v_pk_mul_f32 v[76:77], v[68:69], v[76:77]
	v_pk_mul_f32 v[78:79], v[78:79], v[74:75]
	v_pk_mul_f32 v[80:81], v[80:81], v[76:77]
	v_cvt_pk_bf16_f32 v70, v78, v79
	v_cvt_pk_bf16_f32 v71, v80, v81
	global_store_dwordx2 v125, v[70:71], s[38:39] offset:64
	s_waitcnt vmcnt(15)
	v_lshlrev_b32_e32 v66, 16, v108
	v_and_b32_e32 v67, 0xffff0000, v108
	v_lshlrev_b32_e32 v68, 16, v109
	v_and_b32_e32 v69, 0xffff0000, v109
	v_mul_f32_e32 v70, 0xbfb8aa3b, v66
	v_mul_f32_e32 v71, 0xbfb8aa3b, v67
	v_mul_f32_e32 v72, 0xbfb8aa3b, v68
	v_mul_f32_e32 v73, 0xbfb8aa3b, v69
	v_exp_f32_e32 v70, v70
	v_exp_f32_e32 v71, v71
	v_exp_f32_e32 v72, v72
	v_exp_f32_e32 v73, v73
	v_pk_mul_f32 v[78:79], v[18:19], v[120:121] op_sel_hi:[1,0]
	v_pk_add_f32 v[70:71], v[70:71], 1.0 op_sel_hi:[1,0]
	v_pk_add_f32 v[72:73], v[72:73], 1.0 op_sel_hi:[1,0]
	v_rcp_f32_e32 v74, v70
	v_rcp_f32_e32 v75, v71
	v_rcp_f32_e32 v76, v72
	v_rcp_f32_e32 v77, v73
	v_pk_mul_f32 v[80:81], v[20:21], v[120:121] op_sel_hi:[1,0]
	v_pk_mul_f32 v[74:75], v[66:67], v[74:75]
	v_pk_mul_f32 v[76:77], v[68:69], v[76:77]
	v_pk_mul_f32 v[78:79], v[78:79], v[74:75]
	v_pk_mul_f32 v[80:81], v[80:81], v[76:77]
	v_cvt_pk_bf16_f32 v70, v78, v79
	v_cvt_pk_bf16_f32 v71, v80, v81
	global_store_dwordx2 v125, v[70:71], s[38:39] offset:96
	s_waitcnt vmcnt(15)
	v_lshlrev_b32_e32 v66, 16, v110
	v_and_b32_e32 v67, 0xffff0000, v110
	v_lshlrev_b32_e32 v68, 16, v111
	v_and_b32_e32 v69, 0xffff0000, v111
	v_mul_f32_e32 v70, 0xbfb8aa3b, v66
	v_mul_f32_e32 v71, 0xbfb8aa3b, v67
	v_mul_f32_e32 v72, 0xbfb8aa3b, v68
	v_mul_f32_e32 v73, 0xbfb8aa3b, v69
	v_exp_f32_e32 v70, v70
	v_exp_f32_e32 v71, v71
	v_exp_f32_e32 v72, v72
	v_exp_f32_e32 v73, v73
	v_pk_mul_f32 v[78:79], v[14:15], v[120:121] op_sel_hi:[1,0]
	v_pk_add_f32 v[70:71], v[70:71], 1.0 op_sel_hi:[1,0]
	v_pk_add_f32 v[72:73], v[72:73], 1.0 op_sel_hi:[1,0]
	v_rcp_f32_e32 v74, v70
	v_rcp_f32_e32 v75, v71
	v_rcp_f32_e32 v76, v72
	v_rcp_f32_e32 v77, v73
	v_pk_mul_f32 v[80:81], v[16:17], v[120:121] op_sel_hi:[1,0]
	v_pk_mul_f32 v[74:75], v[66:67], v[74:75]
	v_pk_mul_f32 v[76:77], v[68:69], v[76:77]
	v_pk_mul_f32 v[78:79], v[78:79], v[74:75]
	v_pk_mul_f32 v[80:81], v[80:81], v[76:77]
	v_cvt_pk_bf16_f32 v70, v78, v79
	v_cvt_pk_bf16_f32 v71, v80, v81
	global_store_dwordx2 v125, v[70:71], s[38:39] offset:128
	s_waitcnt vmcnt(15)
	v_lshlrev_b32_e32 v66, 16, v112
	v_and_b32_e32 v67, 0xffff0000, v112
	v_lshlrev_b32_e32 v68, 16, v113
	v_and_b32_e32 v69, 0xffff0000, v113
	v_mul_f32_e32 v70, 0xbfb8aa3b, v66
	v_mul_f32_e32 v71, 0xbfb8aa3b, v67
	v_mul_f32_e32 v72, 0xbfb8aa3b, v68
	v_mul_f32_e32 v73, 0xbfb8aa3b, v69
	v_exp_f32_e32 v70, v70
	v_exp_f32_e32 v71, v71
	v_exp_f32_e32 v72, v72
	v_exp_f32_e32 v73, v73
	v_pk_mul_f32 v[78:79], v[10:11], v[120:121] op_sel_hi:[1,0]
	v_pk_add_f32 v[70:71], v[70:71], 1.0 op_sel_hi:[1,0]
	v_pk_add_f32 v[72:73], v[72:73], 1.0 op_sel_hi:[1,0]
	v_rcp_f32_e32 v74, v70
	v_rcp_f32_e32 v75, v71
	v_rcp_f32_e32 v76, v72
	v_rcp_f32_e32 v77, v73
	v_pk_mul_f32 v[80:81], v[12:13], v[120:121] op_sel_hi:[1,0]
	v_pk_mul_f32 v[74:75], v[66:67], v[74:75]
	v_pk_mul_f32 v[76:77], v[68:69], v[76:77]
	v_pk_mul_f32 v[78:79], v[78:79], v[74:75]
	v_pk_mul_f32 v[80:81], v[80:81], v[76:77]
	v_cvt_pk_bf16_f32 v70, v78, v79
	v_cvt_pk_bf16_f32 v71, v80, v81
	global_store_dwordx2 v125, v[70:71], s[38:39] offset:160
	s_waitcnt vmcnt(15)
	v_lshlrev_b32_e32 v66, 16, v114
	v_and_b32_e32 v67, 0xffff0000, v114
	v_lshlrev_b32_e32 v68, 16, v115
	v_and_b32_e32 v69, 0xffff0000, v115
	v_mul_f32_e32 v70, 0xbfb8aa3b, v66
	v_mul_f32_e32 v71, 0xbfb8aa3b, v67
	v_mul_f32_e32 v72, 0xbfb8aa3b, v68
	v_mul_f32_e32 v73, 0xbfb8aa3b, v69
	v_exp_f32_e32 v70, v70
	v_exp_f32_e32 v71, v71
	v_exp_f32_e32 v72, v72
	v_exp_f32_e32 v73, v73
	v_pk_mul_f32 v[78:79], v[6:7], v[120:121] op_sel_hi:[1,0]
	v_pk_add_f32 v[70:71], v[70:71], 1.0 op_sel_hi:[1,0]
	v_pk_add_f32 v[72:73], v[72:73], 1.0 op_sel_hi:[1,0]
	v_rcp_f32_e32 v74, v70
	v_rcp_f32_e32 v75, v71
	v_rcp_f32_e32 v76, v72
	v_rcp_f32_e32 v77, v73
	v_pk_mul_f32 v[80:81], v[8:9], v[120:121] op_sel_hi:[1,0]
	v_pk_mul_f32 v[74:75], v[66:67], v[74:75]
	v_pk_mul_f32 v[76:77], v[68:69], v[76:77]
	v_pk_mul_f32 v[78:79], v[78:79], v[74:75]
	v_pk_mul_f32 v[80:81], v[80:81], v[76:77]
	v_cvt_pk_bf16_f32 v70, v78, v79
	v_cvt_pk_bf16_f32 v71, v80, v81
	global_store_dwordx2 v125, v[70:71], s[38:39] offset:192
	s_waitcnt vmcnt(15)
	v_lshlrev_b32_e32 v66, 16, v116
	v_and_b32_e32 v67, 0xffff0000, v116
	v_lshlrev_b32_e32 v68, 16, v117
	v_and_b32_e32 v69, 0xffff0000, v117
	v_mul_f32_e32 v70, 0xbfb8aa3b, v66
	v_mul_f32_e32 v71, 0xbfb8aa3b, v67
	v_mul_f32_e32 v72, 0xbfb8aa3b, v68
	v_mul_f32_e32 v73, 0xbfb8aa3b, v69
	v_exp_f32_e32 v70, v70
	v_exp_f32_e32 v71, v71
	v_exp_f32_e32 v72, v72
	v_exp_f32_e32 v73, v73
	v_pk_mul_f32 v[78:79], v[2:3], v[120:121] op_sel_hi:[1,0]
	v_pk_add_f32 v[70:71], v[70:71], 1.0 op_sel_hi:[1,0]
	v_pk_add_f32 v[72:73], v[72:73], 1.0 op_sel_hi:[1,0]
	v_rcp_f32_e32 v74, v70
	v_rcp_f32_e32 v75, v71
	v_rcp_f32_e32 v76, v72
	v_rcp_f32_e32 v77, v73
	v_pk_mul_f32 v[80:81], v[4:5], v[120:121] op_sel_hi:[1,0]
	v_pk_mul_f32 v[74:75], v[66:67], v[74:75]
	v_pk_mul_f32 v[76:77], v[68:69], v[76:77]
	v_pk_mul_f32 v[78:79], v[78:79], v[74:75]
	v_pk_mul_f32 v[80:81], v[80:81], v[76:77]
	v_cvt_pk_bf16_f32 v70, v78, v79
	v_cvt_pk_bf16_f32 v71, v80, v81
	global_store_dwordx2 v125, v[70:71], s[38:39] offset:224
	v_readlane_b32 s0, v236, 9
	s_add_i32 s40, s40, s0
	v_readlane_b32 s1, v236, 10
	s_cmpk_gt_i32 s40, 0xff
	s_cbranch_scc1 .LBB0_401
